# V tile epilogue (in-proj and context projection): 4x4 transposes in lane quads (DPP) + row/register exchange (permlane swaps), 32 eight-byte stores per wave covering whole 128-byte lines instead of 12
# speedup vs baseline: 1.0117x; 1.0117x over previous
.LBB0_215:
	s_andn2_b64 vcc, exec, s[10:11]
	s_cbranch_vccnz .LBB0_217
	s_lshl_b32 s4, s7, 5
	s_lshl_b32 s5, s5, 8
	s_or_b32 s4, s4, s5
	s_lshl_b32 s5, s6, 9
	s_mul_i32 s7, s6, 0xffffffef
	s_or_b32 s4, s4, s5
	s_add_i32 s7, s8, s7
	v_or_b32_e32 v128, s4, v148
	s_movk_i32 s4, 0x2200
	v_lshl_add_u32 v130, s7, 8, v144
	v_mul_lo_u32 v128, v128, s4
	v_mov_b32_e32 v129, 0
	v_ashrrev_i32_e32 v131, 31, v130
	v_lshl_add_u64 v[132:133], s[76:77], 0, v[128:129]
	v_lshl_add_u64 v[130:131], v[130:131], 1, v[132:133]
	v_bfe_u32 v172, v217, 3, 1
	v_mul_u32_u24_e32 v172, 0x21f0, v172
	v_and_b32_e32 v180, 3, v217
	v_mul_u32_u24_e32 v180, 14, v180
	v_add_u32_e32 v172, v172, v180
	v_bfe_u32 v180, v217, 4, 2
	v_mul_i32_i24_e32 v181, 0xfffef000, v180
	v_add_u32_e32 v172, v172, v181
	v_and_b32_e32 v181, 1, v180
	v_mul_u32_u24_e32 v181, 0x4400, v181
	v_add_u32_e32 v172, v172, v181
	v_lshrrev_b32_e32 v181, 1, v180
	v_lshl_add_u32 v172, v181, 6, v172
	v_ashrrev_i32_e32 v173, 31, v172
	v_lshl_add_u64 v[174:175], v[130:131], 0, v[172:173]
	v_and_b32_e32 v180, 1, v217
	v_cmp_ne_u32_e32 vcc, 0, v180
	v_mov_b32_e32 v182, 0x5040100
	v_mov_b32_e32 v183, 0x3020706
	v_cndmask_b32_e32 v182, v182, v183, vcc
	v_and_b32_e32 v180, 2, v217
	v_cmp_ne_u32_e32 vcc, 0, v180
	v_mov_b32_e32 v181, 0
	v_mov_b32_e32 v180, 0x0
	v_lshl_add_u64 v[176:177], v[174:175], 0, v[180:181]
	v_mov_b32_e32 v180, 0x11000
	v_lshl_add_u64 v[178:179], v[174:175], 0, v[180:181]
	v_mov_b32_e32 v180, 0x22000
	v_lshl_add_u64 v[184:185], v[174:175], 0, v[180:181]
	v_mov_b32_e32 v180, 0x33000
	v_lshl_add_u64 v[186:187], v[174:175], 0, v[180:181]
	v_cvt_pk_bf16_f32 v124, v124, v125
	v_cvt_pk_bf16_f32 v126, v126, v127
	v_cvt_pk_bf16_f32 v120, v120, v121
	v_cvt_pk_bf16_f32 v122, v122, v123
	v_mov_b32_dpp v125, v124 quad_perm:[1,0,3,2] row_mask:0xf bank_mask:0xf
	v_mov_b32_dpp v127, v126 quad_perm:[1,0,3,2] row_mask:0xf bank_mask:0xf
	v_mov_b32_dpp v121, v120 quad_perm:[1,0,3,2] row_mask:0xf bank_mask:0xf
	v_mov_b32_dpp v123, v122 quad_perm:[1,0,3,2] row_mask:0xf bank_mask:0xf
	v_perm_b32 v124, v125, v124, v182
	v_perm_b32 v126, v127, v126, v182
	v_perm_b32 v120, v121, v120, v182
	v_perm_b32 v122, v123, v122, v182
	v_cndmask_b32_e32 v125, v126, v124, vcc
	v_cndmask_b32_e32 v121, v122, v120, vcc
	s_nop 1
	v_mov_b32_dpp v127, v125 quad_perm:[2,3,0,1] row_mask:0xf bank_mask:0xf
	v_mov_b32_dpp v123, v121 quad_perm:[2,3,0,1] row_mask:0xf bank_mask:0xf
	v_cndmask_b32_e32 v124, v124, v127, vcc
	v_cndmask_b32_e32 v125, v127, v126, vcc
	v_cndmask_b32_e32 v120, v120, v123, vcc
	v_cndmask_b32_e32 v121, v123, v122, vcc
	v_cvt_pk_bf16_f32 v116, v116, v117
	v_cvt_pk_bf16_f32 v118, v118, v119
	v_cvt_pk_bf16_f32 v112, v112, v113
	v_cvt_pk_bf16_f32 v114, v114, v115
	v_mov_b32_dpp v117, v116 quad_perm:[1,0,3,2] row_mask:0xf bank_mask:0xf
	v_mov_b32_dpp v119, v118 quad_perm:[1,0,3,2] row_mask:0xf bank_mask:0xf
	v_mov_b32_dpp v113, v112 quad_perm:[1,0,3,2] row_mask:0xf bank_mask:0xf
	v_mov_b32_dpp v115, v114 quad_perm:[1,0,3,2] row_mask:0xf bank_mask:0xf
	v_perm_b32 v116, v117, v116, v182
	v_perm_b32 v118, v119, v118, v182
	v_perm_b32 v112, v113, v112, v182
	v_perm_b32 v114, v115, v114, v182
	v_cndmask_b32_e32 v117, v118, v116, vcc
	v_cndmask_b32_e32 v113, v114, v112, vcc
	s_nop 1
	v_mov_b32_dpp v119, v117 quad_perm:[2,3,0,1] row_mask:0xf bank_mask:0xf
	v_mov_b32_dpp v115, v113 quad_perm:[2,3,0,1] row_mask:0xf bank_mask:0xf
	v_cndmask_b32_e32 v116, v116, v119, vcc
	v_cndmask_b32_e32 v117, v119, v118, vcc
	v_cndmask_b32_e32 v112, v112, v115, vcc
	v_cndmask_b32_e32 v113, v115, v114, vcc
	s_nop 1
	v_permlane32_swap_b32_e32 v124, v116
	v_permlane32_swap_b32_e32 v120, v112
	v_permlane32_swap_b32_e32 v125, v117
	v_permlane32_swap_b32_e32 v121, v113
	v_permlane16_swap_b32_e32 v124, v120
	v_permlane16_swap_b32_e32 v116, v112
	v_permlane16_swap_b32_e32 v125, v121
	v_permlane16_swap_b32_e32 v117, v113
	global_store_dwordx2 v[176:177], v[124:125], off
	global_store_dwordx2 v[178:179], v[120:121], off
	global_store_dwordx2 v[184:185], v[116:117], off
	global_store_dwordx2 v[186:187], v[112:113], off
	v_cvt_pk_bf16_f32 v108, v108, v109
	v_cvt_pk_bf16_f32 v110, v110, v111
	v_cvt_pk_bf16_f32 v104, v104, v105
	v_cvt_pk_bf16_f32 v106, v106, v107
	v_mov_b32_dpp v109, v108 quad_perm:[1,0,3,2] row_mask:0xf bank_mask:0xf
	v_mov_b32_dpp v111, v110 quad_perm:[1,0,3,2] row_mask:0xf bank_mask:0xf
	v_mov_b32_dpp v105, v104 quad_perm:[1,0,3,2] row_mask:0xf bank_mask:0xf
	v_mov_b32_dpp v107, v106 quad_perm:[1,0,3,2] row_mask:0xf bank_mask:0xf
	v_perm_b32 v108, v109, v108, v182
	v_perm_b32 v110, v111, v110, v182
	v_perm_b32 v104, v105, v104, v182
	v_perm_b32 v106, v107, v106, v182
	v_cndmask_b32_e32 v109, v110, v108, vcc
	v_cndmask_b32_e32 v105, v106, v104, vcc
	s_nop 1
	v_mov_b32_dpp v111, v109 quad_perm:[2,3,0,1] row_mask:0xf bank_mask:0xf
	v_mov_b32_dpp v107, v105 quad_perm:[2,3,0,1] row_mask:0xf bank_mask:0xf
	v_cndmask_b32_e32 v108, v108, v111, vcc
	v_cndmask_b32_e32 v109, v111, v110, vcc
	v_cndmask_b32_e32 v104, v104, v107, vcc
	v_cndmask_b32_e32 v105, v107, v106, vcc
	v_cvt_pk_bf16_f32 v100, v100, v101
	v_cvt_pk_bf16_f32 v102, v102, v103
	v_cvt_pk_bf16_f32 v96, v96, v97
	v_cvt_pk_bf16_f32 v98, v98, v99
	v_mov_b32_dpp v101, v100 quad_perm:[1,0,3,2] row_mask:0xf bank_mask:0xf
	v_mov_b32_dpp v103, v102 quad_perm:[1,0,3,2] row_mask:0xf bank_mask:0xf
	v_mov_b32_dpp v97, v96 quad_perm:[1,0,3,2] row_mask:0xf bank_mask:0xf
	v_mov_b32_dpp v99, v98 quad_perm:[1,0,3,2] row_mask:0xf bank_mask:0xf
	v_perm_b32 v100, v101, v100, v182
	v_perm_b32 v102, v103, v102, v182
	v_perm_b32 v96, v97, v96, v182
	v_perm_b32 v98, v99, v98, v182
	v_cndmask_b32_e32 v101, v102, v100, vcc
	v_cndmask_b32_e32 v97, v98, v96, vcc
	s_nop 1
	v_mov_b32_dpp v103, v101 quad_perm:[2,3,0,1] row_mask:0xf bank_mask:0xf
	v_mov_b32_dpp v99, v97 quad_perm:[2,3,0,1] row_mask:0xf bank_mask:0xf
	v_cndmask_b32_e32 v100, v100, v103, vcc
	v_cndmask_b32_e32 v101, v103, v102, vcc
	v_cndmask_b32_e32 v96, v96, v99, vcc
	v_cndmask_b32_e32 v97, v99, v98, vcc
	s_nop 1
	v_permlane32_swap_b32_e32 v108, v100
	v_permlane32_swap_b32_e32 v104, v96
	v_permlane32_swap_b32_e32 v109, v101
	v_permlane32_swap_b32_e32 v105, v97
	v_permlane16_swap_b32_e32 v108, v104
	v_permlane16_swap_b32_e32 v100, v96
	v_permlane16_swap_b32_e32 v109, v105
	v_permlane16_swap_b32_e32 v101, v97
	global_store_dwordx2 v[176:177], v[108:109], off offset:256
	global_store_dwordx2 v[178:179], v[104:105], off offset:256
	global_store_dwordx2 v[184:185], v[100:101], off offset:256
	global_store_dwordx2 v[186:187], v[96:97], off offset:256
	v_mov_b32_e32 v180, 0x8800
	v_lshl_add_u64 v[176:177], v[174:175], 0, v[180:181]
	v_mov_b32_e32 v180, 0x19800
	v_lshl_add_u64 v[178:179], v[174:175], 0, v[180:181]
	v_mov_b32_e32 v180, 0x2a800
	v_lshl_add_u64 v[184:185], v[174:175], 0, v[180:181]
	v_mov_b32_e32 v180, 0x3b800
	v_lshl_add_u64 v[186:187], v[174:175], 0, v[180:181]
	v_cvt_pk_bf16_f32 v92, v92, v93
	v_cvt_pk_bf16_f32 v94, v94, v95
	v_cvt_pk_bf16_f32 v88, v88, v89
	v_cvt_pk_bf16_f32 v90, v90, v91
	v_mov_b32_dpp v93, v92 quad_perm:[1,0,3,2] row_mask:0xf bank_mask:0xf
	v_mov_b32_dpp v95, v94 quad_perm:[1,0,3,2] row_mask:0xf bank_mask:0xf
	v_mov_b32_dpp v89, v88 quad_perm:[1,0,3,2] row_mask:0xf bank_mask:0xf
	v_mov_b32_dpp v91, v90 quad_perm:[1,0,3,2] row_mask:0xf bank_mask:0xf
	v_perm_b32 v92, v93, v92, v182
	v_perm_b32 v94, v95, v94, v182
	v_perm_b32 v88, v89, v88, v182
	v_perm_b32 v90, v91, v90, v182
	v_cndmask_b32_e32 v93, v94, v92, vcc
	v_cndmask_b32_e32 v89, v90, v88, vcc
	s_nop 1
	v_mov_b32_dpp v95, v93 quad_perm:[2,3,0,1] row_mask:0xf bank_mask:0xf
	v_mov_b32_dpp v91, v89 quad_perm:[2,3,0,1] row_mask:0xf bank_mask:0xf
	v_cndmask_b32_e32 v92, v92, v95, vcc
	v_cndmask_b32_e32 v93, v95, v94, vcc
	v_cndmask_b32_e32 v88, v88, v91, vcc
	v_cndmask_b32_e32 v89, v91, v90, vcc
	v_cvt_pk_bf16_f32 v84, v84, v85
	v_cvt_pk_bf16_f32 v86, v86, v87
	v_cvt_pk_bf16_f32 v80, v80, v81
	v_cvt_pk_bf16_f32 v82, v82, v83
	v_mov_b32_dpp v85, v84 quad_perm:[1,0,3,2] row_mask:0xf bank_mask:0xf
	v_mov_b32_dpp v87, v86 quad_perm:[1,0,3,2] row_mask:0xf bank_mask:0xf
	v_mov_b32_dpp v81, v80 quad_perm:[1,0,3,2] row_mask:0xf bank_mask:0xf
	v_mov_b32_dpp v83, v82 quad_perm:[1,0,3,2] row_mask:0xf bank_mask:0xf
	v_perm_b32 v84, v85, v84, v182
	v_perm_b32 v86, v87, v86, v182
	v_perm_b32 v80, v81, v80, v182
	v_perm_b32 v82, v83, v82, v182
	v_cndmask_b32_e32 v85, v86, v84, vcc
	v_cndmask_b32_e32 v81, v82, v80, vcc
	s_nop 1
	v_mov_b32_dpp v87, v85 quad_perm:[2,3,0,1] row_mask:0xf bank_mask:0xf
	v_mov_b32_dpp v83, v81 quad_perm:[2,3,0,1] row_mask:0xf bank_mask:0xf
	v_cndmask_b32_e32 v84, v84, v87, vcc
	v_cndmask_b32_e32 v85, v87, v86, vcc
	v_cndmask_b32_e32 v80, v80, v83, vcc
	v_cndmask_b32_e32 v81, v83, v82, vcc
	s_nop 1
	v_permlane32_swap_b32_e32 v92, v84
	v_permlane32_swap_b32_e32 v88, v80
	v_permlane32_swap_b32_e32 v93, v85
	v_permlane32_swap_b32_e32 v89, v81
	v_permlane16_swap_b32_e32 v92, v88
	v_permlane16_swap_b32_e32 v84, v80
	v_permlane16_swap_b32_e32 v93, v89
	v_permlane16_swap_b32_e32 v85, v81
	global_store_dwordx2 v[176:177], v[92:93], off
	global_store_dwordx2 v[178:179], v[88:89], off
	global_store_dwordx2 v[184:185], v[84:85], off
	global_store_dwordx2 v[186:187], v[80:81], off
	v_cvt_pk_bf16_f32 v76, v76, v77
	v_cvt_pk_bf16_f32 v78, v78, v79
	v_cvt_pk_bf16_f32 v72, v72, v73
	v_cvt_pk_bf16_f32 v74, v74, v75
	v_mov_b32_dpp v77, v76 quad_perm:[1,0,3,2] row_mask:0xf bank_mask:0xf
	v_mov_b32_dpp v79, v78 quad_perm:[1,0,3,2] row_mask:0xf bank_mask:0xf
	v_mov_b32_dpp v73, v72 quad_perm:[1,0,3,2] row_mask:0xf bank_mask:0xf
	v_mov_b32_dpp v75, v74 quad_perm:[1,0,3,2] row_mask:0xf bank_mask:0xf
	v_perm_b32 v76, v77, v76, v182
	v_perm_b32 v78, v79, v78, v182
	v_perm_b32 v72, v73, v72, v182
	v_perm_b32 v74, v75, v74, v182
	v_cndmask_b32_e32 v77, v78, v76, vcc
	v_cndmask_b32_e32 v73, v74, v72, vcc
	s_nop 1
	v_mov_b32_dpp v79, v77 quad_perm:[2,3,0,1] row_mask:0xf bank_mask:0xf
	v_mov_b32_dpp v75, v73 quad_perm:[2,3,0,1] row_mask:0xf bank_mask:0xf
	v_cndmask_b32_e32 v76, v76, v79, vcc
	v_cndmask_b32_e32 v77, v79, v78, vcc
	v_cndmask_b32_e32 v72, v72, v75, vcc
	v_cndmask_b32_e32 v73, v75, v74, vcc
	v_cvt_pk_bf16_f32 v68, v68, v69
	v_cvt_pk_bf16_f32 v70, v70, v71
	v_cvt_pk_bf16_f32 v64, v64, v65
	v_cvt_pk_bf16_f32 v66, v66, v67
	v_mov_b32_dpp v69, v68 quad_perm:[1,0,3,2] row_mask:0xf bank_mask:0xf
	v_mov_b32_dpp v71, v70 quad_perm:[1,0,3,2] row_mask:0xf bank_mask:0xf
	v_mov_b32_dpp v65, v64 quad_perm:[1,0,3,2] row_mask:0xf bank_mask:0xf
	v_mov_b32_dpp v67, v66 quad_perm:[1,0,3,2] row_mask:0xf bank_mask:0xf
	v_perm_b32 v68, v69, v68, v182
	v_perm_b32 v70, v71, v70, v182
	v_perm_b32 v64, v65, v64, v182
	v_perm_b32 v66, v67, v66, v182
	v_cndmask_b32_e32 v69, v70, v68, vcc
	v_cndmask_b32_e32 v65, v66, v64, vcc
	s_nop 1
	v_mov_b32_dpp v71, v69 quad_perm:[2,3,0,1] row_mask:0xf bank_mask:0xf
	v_mov_b32_dpp v67, v65 quad_perm:[2,3,0,1] row_mask:0xf bank_mask:0xf
	v_cndmask_b32_e32 v68, v68, v71, vcc
	v_cndmask_b32_e32 v69, v71, v70, vcc
	v_cndmask_b32_e32 v64, v64, v67, vcc
	v_cndmask_b32_e32 v65, v67, v66, vcc
	s_nop 1
	v_permlane32_swap_b32_e32 v76, v68
	v_permlane32_swap_b32_e32 v72, v64
	v_permlane32_swap_b32_e32 v77, v69
	v_permlane32_swap_b32_e32 v73, v65
	v_permlane16_swap_b32_e32 v76, v72
	v_permlane16_swap_b32_e32 v68, v64
	v_permlane16_swap_b32_e32 v77, v73
	v_permlane16_swap_b32_e32 v69, v65
	global_store_dwordx2 v[176:177], v[76:77], off offset:256
	global_store_dwordx2 v[178:179], v[72:73], off offset:256
	global_store_dwordx2 v[184:185], v[68:69], off offset:256
	global_store_dwordx2 v[186:187], v[64:65], off offset:256
	v_mov_b32_e32 v180, 0x110000
	v_lshl_add_u64 v[176:177], v[174:175], 0, v[180:181]
	v_mov_b32_e32 v180, 0x121000
	v_lshl_add_u64 v[178:179], v[174:175], 0, v[180:181]
	v_mov_b32_e32 v180, 0x132000
	v_lshl_add_u64 v[184:185], v[174:175], 0, v[180:181]
	v_mov_b32_e32 v180, 0x143000
	v_lshl_add_u64 v[186:187], v[174:175], 0, v[180:181]
	v_cvt_pk_bf16_f32 v60, v60, v61
	v_cvt_pk_bf16_f32 v62, v62, v63
	v_cvt_pk_bf16_f32 v56, v56, v57
	v_cvt_pk_bf16_f32 v58, v58, v59
	v_mov_b32_dpp v61, v60 quad_perm:[1,0,3,2] row_mask:0xf bank_mask:0xf
	v_mov_b32_dpp v63, v62 quad_perm:[1,0,3,2] row_mask:0xf bank_mask:0xf
	v_mov_b32_dpp v57, v56 quad_perm:[1,0,3,2] row_mask:0xf bank_mask:0xf
	v_mov_b32_dpp v59, v58 quad_perm:[1,0,3,2] row_mask:0xf bank_mask:0xf
	v_perm_b32 v60, v61, v60, v182
	v_perm_b32 v62, v63, v62, v182
	v_perm_b32 v56, v57, v56, v182
	v_perm_b32 v58, v59, v58, v182
	v_cndmask_b32_e32 v61, v62, v60, vcc
	v_cndmask_b32_e32 v57, v58, v56, vcc
	s_nop 1
	v_mov_b32_dpp v63, v61 quad_perm:[2,3,0,1] row_mask:0xf bank_mask:0xf
	v_mov_b32_dpp v59, v57 quad_perm:[2,3,0,1] row_mask:0xf bank_mask:0xf
	v_cndmask_b32_e32 v60, v60, v63, vcc
	v_cndmask_b32_e32 v61, v63, v62, vcc
	v_cndmask_b32_e32 v56, v56, v59, vcc
	v_cndmask_b32_e32 v57, v59, v58, vcc
	v_cvt_pk_bf16_f32 v52, v52, v53
	v_cvt_pk_bf16_f32 v54, v54, v55
	v_cvt_pk_bf16_f32 v48, v48, v49
	v_cvt_pk_bf16_f32 v50, v50, v51
	v_mov_b32_dpp v53, v52 quad_perm:[1,0,3,2] row_mask:0xf bank_mask:0xf
	v_mov_b32_dpp v55, v54 quad_perm:[1,0,3,2] row_mask:0xf bank_mask:0xf
	v_mov_b32_dpp v49, v48 quad_perm:[1,0,3,2] row_mask:0xf bank_mask:0xf
	v_mov_b32_dpp v51, v50 quad_perm:[1,0,3,2] row_mask:0xf bank_mask:0xf
	v_perm_b32 v52, v53, v52, v182
	v_perm_b32 v54, v55, v54, v182
	v_perm_b32 v48, v49, v48, v182
	v_perm_b32 v50, v51, v50, v182
	v_cndmask_b32_e32 v53, v54, v52, vcc
	v_cndmask_b32_e32 v49, v50, v48, vcc
	s_nop 1
	v_mov_b32_dpp v55, v53 quad_perm:[2,3,0,1] row_mask:0xf bank_mask:0xf
	v_mov_b32_dpp v51, v49 quad_perm:[2,3,0,1] row_mask:0xf bank_mask:0xf
	v_cndmask_b32_e32 v52, v52, v55, vcc
	v_cndmask_b32_e32 v53, v55, v54, vcc
	v_cndmask_b32_e32 v48, v48, v51, vcc
	v_cndmask_b32_e32 v49, v51, v50, vcc
	s_nop 1
	v_permlane32_swap_b32_e32 v60, v52
	v_permlane32_swap_b32_e32 v56, v48
	v_permlane32_swap_b32_e32 v61, v53
	v_permlane32_swap_b32_e32 v57, v49
	v_permlane16_swap_b32_e32 v60, v56
	v_permlane16_swap_b32_e32 v52, v48
	v_permlane16_swap_b32_e32 v61, v57
	v_permlane16_swap_b32_e32 v53, v49
	global_store_dwordx2 v[176:177], v[60:61], off
	global_store_dwordx2 v[178:179], v[56:57], off
	global_store_dwordx2 v[184:185], v[52:53], off
	global_store_dwordx2 v[186:187], v[48:49], off
	v_cvt_pk_bf16_f32 v44, v44, v45
	v_cvt_pk_bf16_f32 v46, v46, v47
	v_cvt_pk_bf16_f32 v40, v40, v41
	v_cvt_pk_bf16_f32 v42, v42, v43
	v_mov_b32_dpp v45, v44 quad_perm:[1,0,3,2] row_mask:0xf bank_mask:0xf
	v_mov_b32_dpp v47, v46 quad_perm:[1,0,3,2] row_mask:0xf bank_mask:0xf
	v_mov_b32_dpp v41, v40 quad_perm:[1,0,3,2] row_mask:0xf bank_mask:0xf
	v_mov_b32_dpp v43, v42 quad_perm:[1,0,3,2] row_mask:0xf bank_mask:0xf
	v_perm_b32 v44, v45, v44, v182
	v_perm_b32 v46, v47, v46, v182
	v_perm_b32 v40, v41, v40, v182
	v_perm_b32 v42, v43, v42, v182
	v_cndmask_b32_e32 v45, v46, v44, vcc
	v_cndmask_b32_e32 v41, v42, v40, vcc
	s_nop 1
	v_mov_b32_dpp v47, v45 quad_perm:[2,3,0,1] row_mask:0xf bank_mask:0xf
	v_mov_b32_dpp v43, v41 quad_perm:[2,3,0,1] row_mask:0xf bank_mask:0xf
	v_cndmask_b32_e32 v44, v44, v47, vcc
	v_cndmask_b32_e32 v45, v47, v46, vcc
	v_cndmask_b32_e32 v40, v40, v43, vcc
	v_cndmask_b32_e32 v41, v43, v42, vcc
	v_cvt_pk_bf16_f32 v36, v36, v37
	v_cvt_pk_bf16_f32 v38, v38, v39
	v_cvt_pk_bf16_f32 v32, v32, v33
	v_cvt_pk_bf16_f32 v34, v34, v35
	v_mov_b32_dpp v37, v36 quad_perm:[1,0,3,2] row_mask:0xf bank_mask:0xf
	v_mov_b32_dpp v39, v38 quad_perm:[1,0,3,2] row_mask:0xf bank_mask:0xf
	v_mov_b32_dpp v33, v32 quad_perm:[1,0,3,2] row_mask:0xf bank_mask:0xf
	v_mov_b32_dpp v35, v34 quad_perm:[1,0,3,2] row_mask:0xf bank_mask:0xf
	v_perm_b32 v36, v37, v36, v182
	v_perm_b32 v38, v39, v38, v182
	v_perm_b32 v32, v33, v32, v182
	v_perm_b32 v34, v35, v34, v182
	v_cndmask_b32_e32 v37, v38, v36, vcc
	v_cndmask_b32_e32 v33, v34, v32, vcc
	s_nop 1
	v_mov_b32_dpp v39, v37 quad_perm:[2,3,0,1] row_mask:0xf bank_mask:0xf
	v_mov_b32_dpp v35, v33 quad_perm:[2,3,0,1] row_mask:0xf bank_mask:0xf
	v_cndmask_b32_e32 v36, v36, v39, vcc
	v_cndmask_b32_e32 v37, v39, v38, vcc
	v_cndmask_b32_e32 v32, v32, v35, vcc
	v_cndmask_b32_e32 v33, v35, v34, vcc
	s_nop 1
	v_permlane32_swap_b32_e32 v44, v36
	v_permlane32_swap_b32_e32 v40, v32
	v_permlane32_swap_b32_e32 v45, v37
	v_permlane32_swap_b32_e32 v41, v33
	v_permlane16_swap_b32_e32 v44, v40
	v_permlane16_swap_b32_e32 v36, v32
	v_permlane16_swap_b32_e32 v45, v41
	v_permlane16_swap_b32_e32 v37, v33
	global_store_dwordx2 v[176:177], v[44:45], off offset:256
	global_store_dwordx2 v[178:179], v[40:41], off offset:256
	global_store_dwordx2 v[184:185], v[36:37], off offset:256
	global_store_dwordx2 v[186:187], v[32:33], off offset:256
	v_mov_b32_e32 v180, 0x118800
	v_lshl_add_u64 v[176:177], v[174:175], 0, v[180:181]
	v_mov_b32_e32 v180, 0x129800
	v_lshl_add_u64 v[178:179], v[174:175], 0, v[180:181]
	v_mov_b32_e32 v180, 0x13a800
	v_lshl_add_u64 v[184:185], v[174:175], 0, v[180:181]
	v_mov_b32_e32 v180, 0x14b800
	v_lshl_add_u64 v[186:187], v[174:175], 0, v[180:181]
	v_cvt_pk_bf16_f32 v28, v28, v29
	v_cvt_pk_bf16_f32 v30, v30, v31
	v_cvt_pk_bf16_f32 v24, v24, v25
	v_cvt_pk_bf16_f32 v26, v26, v27
	v_mov_b32_dpp v29, v28 quad_perm:[1,0,3,2] row_mask:0xf bank_mask:0xf
	v_mov_b32_dpp v31, v30 quad_perm:[1,0,3,2] row_mask:0xf bank_mask:0xf
	v_mov_b32_dpp v25, v24 quad_perm:[1,0,3,2] row_mask:0xf bank_mask:0xf
	v_mov_b32_dpp v27, v26 quad_perm:[1,0,3,2] row_mask:0xf bank_mask:0xf
	v_perm_b32 v28, v29, v28, v182
	v_perm_b32 v30, v31, v30, v182
	v_perm_b32 v24, v25, v24, v182
	v_perm_b32 v26, v27, v26, v182
	v_cndmask_b32_e32 v29, v30, v28, vcc
	v_cndmask_b32_e32 v25, v26, v24, vcc
	s_nop 1
	v_mov_b32_dpp v31, v29 quad_perm:[2,3,0,1] row_mask:0xf bank_mask:0xf
	v_mov_b32_dpp v27, v25 quad_perm:[2,3,0,1] row_mask:0xf bank_mask:0xf
	v_cndmask_b32_e32 v28, v28, v31, vcc
	v_cndmask_b32_e32 v29, v31, v30, vcc
	v_cndmask_b32_e32 v24, v24, v27, vcc
	v_cndmask_b32_e32 v25, v27, v26, vcc
	v_cvt_pk_bf16_f32 v20, v20, v21
	v_cvt_pk_bf16_f32 v22, v22, v23
	v_cvt_pk_bf16_f32 v16, v16, v17
	v_cvt_pk_bf16_f32 v18, v18, v19
	v_mov_b32_dpp v21, v20 quad_perm:[1,0,3,2] row_mask:0xf bank_mask:0xf
	v_mov_b32_dpp v23, v22 quad_perm:[1,0,3,2] row_mask:0xf bank_mask:0xf
	v_mov_b32_dpp v17, v16 quad_perm:[1,0,3,2] row_mask:0xf bank_mask:0xf
	v_mov_b32_dpp v19, v18 quad_perm:[1,0,3,2] row_mask:0xf bank_mask:0xf
	v_perm_b32 v20, v21, v20, v182
	v_perm_b32 v22, v23, v22, v182
	v_perm_b32 v16, v17, v16, v182
	v_perm_b32 v18, v19, v18, v182
	v_cndmask_b32_e32 v21, v22, v20, vcc
	v_cndmask_b32_e32 v17, v18, v16, vcc
	s_nop 1
	v_mov_b32_dpp v23, v21 quad_perm:[2,3,0,1] row_mask:0xf bank_mask:0xf
	v_mov_b32_dpp v19, v17 quad_perm:[2,3,0,1] row_mask:0xf bank_mask:0xf
	v_cndmask_b32_e32 v20, v20, v23, vcc
	v_cndmask_b32_e32 v21, v23, v22, vcc
	v_cndmask_b32_e32 v16, v16, v19, vcc
	v_cndmask_b32_e32 v17, v19, v18, vcc
	s_nop 1
	v_permlane32_swap_b32_e32 v28, v20
	v_permlane32_swap_b32_e32 v24, v16
	v_permlane32_swap_b32_e32 v29, v21
	v_permlane32_swap_b32_e32 v25, v17
	v_permlane16_swap_b32_e32 v28, v24
	v_permlane16_swap_b32_e32 v20, v16
	v_permlane16_swap_b32_e32 v29, v25
	v_permlane16_swap_b32_e32 v21, v17
	global_store_dwordx2 v[176:177], v[28:29], off
	global_store_dwordx2 v[178:179], v[24:25], off
	global_store_dwordx2 v[184:185], v[20:21], off
	global_store_dwordx2 v[186:187], v[16:17], off
	v_cvt_pk_bf16_f32 v12, v12, v13
	v_cvt_pk_bf16_f32 v14, v14, v15
	v_cvt_pk_bf16_f32 v8, v8, v9
	v_cvt_pk_bf16_f32 v10, v10, v11
	v_mov_b32_dpp v13, v12 quad_perm:[1,0,3,2] row_mask:0xf bank_mask:0xf
	v_mov_b32_dpp v15, v14 quad_perm:[1,0,3,2] row_mask:0xf bank_mask:0xf
	v_mov_b32_dpp v9, v8 quad_perm:[1,0,3,2] row_mask:0xf bank_mask:0xf
	v_mov_b32_dpp v11, v10 quad_perm:[1,0,3,2] row_mask:0xf bank_mask:0xf
	v_perm_b32 v12, v13, v12, v182
	v_perm_b32 v14, v15, v14, v182
	v_perm_b32 v8, v9, v8, v182
	v_perm_b32 v10, v11, v10, v182
	v_cndmask_b32_e32 v13, v14, v12, vcc
	v_cndmask_b32_e32 v9, v10, v8, vcc
	s_nop 1
	v_mov_b32_dpp v15, v13 quad_perm:[2,3,0,1] row_mask:0xf bank_mask:0xf
	v_mov_b32_dpp v11, v9 quad_perm:[2,3,0,1] row_mask:0xf bank_mask:0xf
	v_cndmask_b32_e32 v12, v12, v15, vcc
	v_cndmask_b32_e32 v13, v15, v14, vcc
	v_cndmask_b32_e32 v8, v8, v11, vcc
	v_cndmask_b32_e32 v9, v11, v10, vcc
	v_cvt_pk_bf16_f32 v4, v4, v5
	v_cvt_pk_bf16_f32 v6, v6, v7
	v_cvt_pk_bf16_f32 v0, v0, v1
	v_cvt_pk_bf16_f32 v2, v2, v3
	v_mov_b32_dpp v5, v4 quad_perm:[1,0,3,2] row_mask:0xf bank_mask:0xf
	v_mov_b32_dpp v7, v6 quad_perm:[1,0,3,2] row_mask:0xf bank_mask:0xf
	v_mov_b32_dpp v1, v0 quad_perm:[1,0,3,2] row_mask:0xf bank_mask:0xf
	v_mov_b32_dpp v3, v2 quad_perm:[1,0,3,2] row_mask:0xf bank_mask:0xf
	v_perm_b32 v4, v5, v4, v182
	v_perm_b32 v6, v7, v6, v182
	v_perm_b32 v0, v1, v0, v182
	v_perm_b32 v2, v3, v2, v182
	v_cndmask_b32_e32 v5, v6, v4, vcc
	v_cndmask_b32_e32 v1, v2, v0, vcc
	s_nop 1
	v_mov_b32_dpp v7, v5 quad_perm:[2,3,0,1] row_mask:0xf bank_mask:0xf
	v_mov_b32_dpp v3, v1 quad_perm:[2,3,0,1] row_mask:0xf bank_mask:0xf
	v_cndmask_b32_e32 v4, v4, v7, vcc
	v_cndmask_b32_e32 v5, v7, v6, vcc
	v_cndmask_b32_e32 v0, v0, v3, vcc
	v_cndmask_b32_e32 v1, v3, v2, vcc
	s_nop 1
	v_permlane32_swap_b32_e32 v12, v4
	v_permlane32_swap_b32_e32 v8, v0
	v_permlane32_swap_b32_e32 v13, v5
	v_permlane32_swap_b32_e32 v9, v1
	v_permlane16_swap_b32_e32 v12, v8
	v_permlane16_swap_b32_e32 v4, v0
	v_permlane16_swap_b32_e32 v13, v9
	v_permlane16_swap_b32_e32 v5, v1
	global_store_dwordx2 v[176:177], v[12:13], off offset:256
	global_store_dwordx2 v[178:179], v[8:9], off offset:256
	global_store_dwordx2 v[184:185], v[4:5], off offset:256
	global_store_dwordx2 v[186:187], v[0:1], off offset:256

.LBB0_362:
	s_andn2_b64 vcc, exec, s[0:1]
	s_cbranch_vccnz .LBB0_278
	s_mul_hi_i32 s0, s66, 0x78787879
	s_lshr_b32 s1, s0, 31
	s_ashr_i32 s0, s0, 3
	s_add_i32 s0, s0, s1
	s_mul_i32 s1, s0, 0xffffffef
	s_add_i32 s1, s1, s66
	v_lshl_add_u32 v146, s1, 8, v138
	s_ashr_i32 s1, s0, 31
	v_lshl_or_b32 v136, s57, 8, v163
	s_lshl_b64 s[0:1], s[0:1], 9
	v_or_b32_e32 v136, s0, v136
	v_mov_b64_e32 v[144:145], s[76:77]
	v_ashrrev_i32_e32 v147, 31, v146
	v_mad_u64_u32 v[148:149], s[4:5], v136, s96, v[144:145]
	v_mad_i32_i24 v149, s1, v171, v149
	v_lshlrev_b64 v[146:147], 1, v[146:147]
	v_lshl_add_u64 v[148:149], v[148:149], 0, v[146:147]
	v_bfe_u32 v172, v217, 3, 1
	v_mul_u32_u24_e32 v172, 0x21f0, v172
	v_and_b32_e32 v180, 3, v217
	v_mul_u32_u24_e32 v180, 14, v180
	v_add_u32_e32 v172, v172, v180
	v_bfe_u32 v180, v217, 4, 2
	v_mul_i32_i24_e32 v181, 0xfffef000, v180
	v_add_u32_e32 v172, v172, v181
	v_and_b32_e32 v181, 1, v180
	v_mul_u32_u24_e32 v181, 0x4400, v181
	v_add_u32_e32 v172, v172, v181
	v_lshrrev_b32_e32 v181, 1, v180
	v_lshl_add_u32 v172, v181, 6, v172
	v_ashrrev_i32_e32 v173, 31, v172
	v_lshl_add_u64 v[174:175], v[148:149], 0, v[172:173]
	v_and_b32_e32 v180, 1, v217
	v_cmp_ne_u32_e32 vcc, 0, v180
	v_mov_b32_e32 v182, 0x5040100
	v_mov_b32_e32 v183, 0x3020706
	v_cndmask_b32_e32 v182, v182, v183, vcc
	v_and_b32_e32 v180, 2, v217
	v_cmp_ne_u32_e32 vcc, 0, v180
	v_mov_b32_e32 v181, 0
	v_mov_b32_e32 v180, 0x0
	v_lshl_add_u64 v[176:177], v[174:175], 0, v[180:181]
	v_mov_b32_e32 v180, 0x11000
	v_lshl_add_u64 v[178:179], v[174:175], 0, v[180:181]
	v_mov_b32_e32 v180, 0x22000
	v_lshl_add_u64 v[184:185], v[174:175], 0, v[180:181]
	v_mov_b32_e32 v180, 0x33000
	v_lshl_add_u64 v[186:187], v[174:175], 0, v[180:181]
	v_cvt_pk_bf16_f32 v124, v124, v125
	v_cvt_pk_bf16_f32 v126, v126, v127
	v_cvt_pk_bf16_f32 v120, v120, v121
	v_cvt_pk_bf16_f32 v122, v122, v123
	v_mov_b32_dpp v125, v124 quad_perm:[1,0,3,2] row_mask:0xf bank_mask:0xf
	v_mov_b32_dpp v127, v126 quad_perm:[1,0,3,2] row_mask:0xf bank_mask:0xf
	v_mov_b32_dpp v121, v120 quad_perm:[1,0,3,2] row_mask:0xf bank_mask:0xf
	v_mov_b32_dpp v123, v122 quad_perm:[1,0,3,2] row_mask:0xf bank_mask:0xf
	v_perm_b32 v124, v125, v124, v182
	v_perm_b32 v126, v127, v126, v182
	v_perm_b32 v120, v121, v120, v182
	v_perm_b32 v122, v123, v122, v182
	v_cndmask_b32_e32 v125, v126, v124, vcc
	v_cndmask_b32_e32 v121, v122, v120, vcc
	s_nop 1
	v_mov_b32_dpp v127, v125 quad_perm:[2,3,0,1] row_mask:0xf bank_mask:0xf
	v_mov_b32_dpp v123, v121 quad_perm:[2,3,0,1] row_mask:0xf bank_mask:0xf
	v_cndmask_b32_e32 v124, v124, v127, vcc
	v_cndmask_b32_e32 v125, v127, v126, vcc
	v_cndmask_b32_e32 v120, v120, v123, vcc
	v_cndmask_b32_e32 v121, v123, v122, vcc
	v_cvt_pk_bf16_f32 v116, v116, v117
	v_cvt_pk_bf16_f32 v118, v118, v119
	v_cvt_pk_bf16_f32 v112, v112, v113
	v_cvt_pk_bf16_f32 v114, v114, v115
	v_mov_b32_dpp v117, v116 quad_perm:[1,0,3,2] row_mask:0xf bank_mask:0xf
	v_mov_b32_dpp v119, v118 quad_perm:[1,0,3,2] row_mask:0xf bank_mask:0xf
	v_mov_b32_dpp v113, v112 quad_perm:[1,0,3,2] row_mask:0xf bank_mask:0xf
	v_mov_b32_dpp v115, v114 quad_perm:[1,0,3,2] row_mask:0xf bank_mask:0xf
	v_perm_b32 v116, v117, v116, v182
	v_perm_b32 v118, v119, v118, v182
	v_perm_b32 v112, v113, v112, v182
	v_perm_b32 v114, v115, v114, v182
	v_cndmask_b32_e32 v117, v118, v116, vcc
	v_cndmask_b32_e32 v113, v114, v112, vcc
	s_nop 1
	v_mov_b32_dpp v119, v117 quad_perm:[2,3,0,1] row_mask:0xf bank_mask:0xf
	v_mov_b32_dpp v115, v113 quad_perm:[2,3,0,1] row_mask:0xf bank_mask:0xf
	v_cndmask_b32_e32 v116, v116, v119, vcc
	v_cndmask_b32_e32 v117, v119, v118, vcc
	v_cndmask_b32_e32 v112, v112, v115, vcc
	v_cndmask_b32_e32 v113, v115, v114, vcc
	s_nop 1
	v_permlane32_swap_b32_e32 v124, v116
	v_permlane32_swap_b32_e32 v120, v112
	v_permlane32_swap_b32_e32 v125, v117
	v_permlane32_swap_b32_e32 v121, v113
	v_permlane16_swap_b32_e32 v124, v120
	v_permlane16_swap_b32_e32 v116, v112
	v_permlane16_swap_b32_e32 v125, v121
	v_permlane16_swap_b32_e32 v117, v113
	global_store_dwordx2 v[176:177], v[124:125], off
	global_store_dwordx2 v[178:179], v[120:121], off
	global_store_dwordx2 v[184:185], v[116:117], off
	global_store_dwordx2 v[186:187], v[112:113], off
	v_cvt_pk_bf16_f32 v108, v108, v109
	v_cvt_pk_bf16_f32 v110, v110, v111
	v_cvt_pk_bf16_f32 v104, v104, v105
	v_cvt_pk_bf16_f32 v106, v106, v107
	v_mov_b32_dpp v109, v108 quad_perm:[1,0,3,2] row_mask:0xf bank_mask:0xf
	v_mov_b32_dpp v111, v110 quad_perm:[1,0,3,2] row_mask:0xf bank_mask:0xf
	v_mov_b32_dpp v105, v104 quad_perm:[1,0,3,2] row_mask:0xf bank_mask:0xf
	v_mov_b32_dpp v107, v106 quad_perm:[1,0,3,2] row_mask:0xf bank_mask:0xf
	v_perm_b32 v108, v109, v108, v182
	v_perm_b32 v110, v111, v110, v182
	v_perm_b32 v104, v105, v104, v182
	v_perm_b32 v106, v107, v106, v182
	v_cndmask_b32_e32 v109, v110, v108, vcc
	v_cndmask_b32_e32 v105, v106, v104, vcc
	s_nop 1
	v_mov_b32_dpp v111, v109 quad_perm:[2,3,0,1] row_mask:0xf bank_mask:0xf
	v_mov_b32_dpp v107, v105 quad_perm:[2,3,0,1] row_mask:0xf bank_mask:0xf
	v_cndmask_b32_e32 v108, v108, v111, vcc
	v_cndmask_b32_e32 v109, v111, v110, vcc
	v_cndmask_b32_e32 v104, v104, v107, vcc
	v_cndmask_b32_e32 v105, v107, v106, vcc
	v_cvt_pk_bf16_f32 v100, v100, v101
	v_cvt_pk_bf16_f32 v102, v102, v103
	v_cvt_pk_bf16_f32 v96, v96, v97
	v_cvt_pk_bf16_f32 v98, v98, v99
	v_mov_b32_dpp v101, v100 quad_perm:[1,0,3,2] row_mask:0xf bank_mask:0xf
	v_mov_b32_dpp v103, v102 quad_perm:[1,0,3,2] row_mask:0xf bank_mask:0xf
	v_mov_b32_dpp v97, v96 quad_perm:[1,0,3,2] row_mask:0xf bank_mask:0xf
	v_mov_b32_dpp v99, v98 quad_perm:[1,0,3,2] row_mask:0xf bank_mask:0xf
	v_perm_b32 v100, v101, v100, v182
	v_perm_b32 v102, v103, v102, v182
	v_perm_b32 v96, v97, v96, v182
	v_perm_b32 v98, v99, v98, v182
	v_cndmask_b32_e32 v101, v102, v100, vcc
	v_cndmask_b32_e32 v97, v98, v96, vcc
	s_nop 1
	v_mov_b32_dpp v103, v101 quad_perm:[2,3,0,1] row_mask:0xf bank_mask:0xf
	v_mov_b32_dpp v99, v97 quad_perm:[2,3,0,1] row_mask:0xf bank_mask:0xf
	v_cndmask_b32_e32 v100, v100, v103, vcc
	v_cndmask_b32_e32 v101, v103, v102, vcc
	v_cndmask_b32_e32 v96, v96, v99, vcc
	v_cndmask_b32_e32 v97, v99, v98, vcc
	s_nop 1
	v_permlane32_swap_b32_e32 v108, v100
	v_permlane32_swap_b32_e32 v104, v96
	v_permlane32_swap_b32_e32 v109, v101
	v_permlane32_swap_b32_e32 v105, v97
	v_permlane16_swap_b32_e32 v108, v104
	v_permlane16_swap_b32_e32 v100, v96
	v_permlane16_swap_b32_e32 v109, v105
	v_permlane16_swap_b32_e32 v101, v97
	global_store_dwordx2 v[176:177], v[108:109], off offset:256
	global_store_dwordx2 v[178:179], v[104:105], off offset:256
	global_store_dwordx2 v[184:185], v[100:101], off offset:256
	global_store_dwordx2 v[186:187], v[96:97], off offset:256
	v_mov_b32_e32 v180, 0x8800
	v_lshl_add_u64 v[176:177], v[174:175], 0, v[180:181]
	v_mov_b32_e32 v180, 0x19800
	v_lshl_add_u64 v[178:179], v[174:175], 0, v[180:181]
	v_mov_b32_e32 v180, 0x2a800
	v_lshl_add_u64 v[184:185], v[174:175], 0, v[180:181]
	v_mov_b32_e32 v180, 0x3b800
	v_lshl_add_u64 v[186:187], v[174:175], 0, v[180:181]
	v_cvt_pk_bf16_f32 v92, v92, v93
	v_cvt_pk_bf16_f32 v94, v94, v95
	v_cvt_pk_bf16_f32 v88, v88, v89
	v_cvt_pk_bf16_f32 v90, v90, v91
	v_mov_b32_dpp v93, v92 quad_perm:[1,0,3,2] row_mask:0xf bank_mask:0xf
	v_mov_b32_dpp v95, v94 quad_perm:[1,0,3,2] row_mask:0xf bank_mask:0xf
	v_mov_b32_dpp v89, v88 quad_perm:[1,0,3,2] row_mask:0xf bank_mask:0xf
	v_mov_b32_dpp v91, v90 quad_perm:[1,0,3,2] row_mask:0xf bank_mask:0xf
	v_perm_b32 v92, v93, v92, v182
	v_perm_b32 v94, v95, v94, v182
	v_perm_b32 v88, v89, v88, v182
	v_perm_b32 v90, v91, v90, v182
	v_cndmask_b32_e32 v93, v94, v92, vcc
	v_cndmask_b32_e32 v89, v90, v88, vcc
	s_nop 1
	v_mov_b32_dpp v95, v93 quad_perm:[2,3,0,1] row_mask:0xf bank_mask:0xf
	v_mov_b32_dpp v91, v89 quad_perm:[2,3,0,1] row_mask:0xf bank_mask:0xf
	v_cndmask_b32_e32 v92, v92, v95, vcc
	v_cndmask_b32_e32 v93, v95, v94, vcc
	v_cndmask_b32_e32 v88, v88, v91, vcc
	v_cndmask_b32_e32 v89, v91, v90, vcc
	v_cvt_pk_bf16_f32 v84, v84, v85
	v_cvt_pk_bf16_f32 v86, v86, v87
	v_cvt_pk_bf16_f32 v80, v80, v81
	v_cvt_pk_bf16_f32 v82, v82, v83
	v_mov_b32_dpp v85, v84 quad_perm:[1,0,3,2] row_mask:0xf bank_mask:0xf
	v_mov_b32_dpp v87, v86 quad_perm:[1,0,3,2] row_mask:0xf bank_mask:0xf
	v_mov_b32_dpp v81, v80 quad_perm:[1,0,3,2] row_mask:0xf bank_mask:0xf
	v_mov_b32_dpp v83, v82 quad_perm:[1,0,3,2] row_mask:0xf bank_mask:0xf
	v_perm_b32 v84, v85, v84, v182
	v_perm_b32 v86, v87, v86, v182
	v_perm_b32 v80, v81, v80, v182
	v_perm_b32 v82, v83, v82, v182
	v_cndmask_b32_e32 v85, v86, v84, vcc
	v_cndmask_b32_e32 v81, v82, v80, vcc
	s_nop 1
	v_mov_b32_dpp v87, v85 quad_perm:[2,3,0,1] row_mask:0xf bank_mask:0xf
	v_mov_b32_dpp v83, v81 quad_perm:[2,3,0,1] row_mask:0xf bank_mask:0xf
	v_cndmask_b32_e32 v84, v84, v87, vcc
	v_cndmask_b32_e32 v85, v87, v86, vcc
	v_cndmask_b32_e32 v80, v80, v83, vcc
	v_cndmask_b32_e32 v81, v83, v82, vcc
	s_nop 1
	v_permlane32_swap_b32_e32 v92, v84
	v_permlane32_swap_b32_e32 v88, v80
	v_permlane32_swap_b32_e32 v93, v85
	v_permlane32_swap_b32_e32 v89, v81
	v_permlane16_swap_b32_e32 v92, v88
	v_permlane16_swap_b32_e32 v84, v80
	v_permlane16_swap_b32_e32 v93, v89
	v_permlane16_swap_b32_e32 v85, v81
	global_store_dwordx2 v[176:177], v[92:93], off
	global_store_dwordx2 v[178:179], v[88:89], off
	global_store_dwordx2 v[184:185], v[84:85], off
	global_store_dwordx2 v[186:187], v[80:81], off
	v_cvt_pk_bf16_f32 v76, v76, v77
	v_cvt_pk_bf16_f32 v78, v78, v79
	v_cvt_pk_bf16_f32 v72, v72, v73
	v_cvt_pk_bf16_f32 v74, v74, v75
	v_mov_b32_dpp v77, v76 quad_perm:[1,0,3,2] row_mask:0xf bank_mask:0xf
	v_mov_b32_dpp v79, v78 quad_perm:[1,0,3,2] row_mask:0xf bank_mask:0xf
	v_mov_b32_dpp v73, v72 quad_perm:[1,0,3,2] row_mask:0xf bank_mask:0xf
	v_mov_b32_dpp v75, v74 quad_perm:[1,0,3,2] row_mask:0xf bank_mask:0xf
	v_perm_b32 v76, v77, v76, v182
	v_perm_b32 v78, v79, v78, v182
	v_perm_b32 v72, v73, v72, v182
	v_perm_b32 v74, v75, v74, v182
	v_cndmask_b32_e32 v77, v78, v76, vcc
	v_cndmask_b32_e32 v73, v74, v72, vcc
	s_nop 1
	v_mov_b32_dpp v79, v77 quad_perm:[2,3,0,1] row_mask:0xf bank_mask:0xf
	v_mov_b32_dpp v75, v73 quad_perm:[2,3,0,1] row_mask:0xf bank_mask:0xf
	v_cndmask_b32_e32 v76, v76, v79, vcc
	v_cndmask_b32_e32 v77, v79, v78, vcc
	v_cndmask_b32_e32 v72, v72, v75, vcc
	v_cndmask_b32_e32 v73, v75, v74, vcc
	v_cvt_pk_bf16_f32 v68, v68, v69
	v_cvt_pk_bf16_f32 v70, v70, v71
	v_cvt_pk_bf16_f32 v64, v64, v65
	v_cvt_pk_bf16_f32 v66, v66, v67
	v_mov_b32_dpp v69, v68 quad_perm:[1,0,3,2] row_mask:0xf bank_mask:0xf
	v_mov_b32_dpp v71, v70 quad_perm:[1,0,3,2] row_mask:0xf bank_mask:0xf
	v_mov_b32_dpp v65, v64 quad_perm:[1,0,3,2] row_mask:0xf bank_mask:0xf
	v_mov_b32_dpp v67, v66 quad_perm:[1,0,3,2] row_mask:0xf bank_mask:0xf
	v_perm_b32 v68, v69, v68, v182
	v_perm_b32 v70, v71, v70, v182
	v_perm_b32 v64, v65, v64, v182
	v_perm_b32 v66, v67, v66, v182
	v_cndmask_b32_e32 v69, v70, v68, vcc
	v_cndmask_b32_e32 v65, v66, v64, vcc
	s_nop 1
	v_mov_b32_dpp v71, v69 quad_perm:[2,3,0,1] row_mask:0xf bank_mask:0xf
	v_mov_b32_dpp v67, v65 quad_perm:[2,3,0,1] row_mask:0xf bank_mask:0xf
	v_cndmask_b32_e32 v68, v68, v71, vcc
	v_cndmask_b32_e32 v69, v71, v70, vcc
	v_cndmask_b32_e32 v64, v64, v67, vcc
	v_cndmask_b32_e32 v65, v67, v66, vcc
	s_nop 1
	v_permlane32_swap_b32_e32 v76, v68
	v_permlane32_swap_b32_e32 v72, v64
	v_permlane32_swap_b32_e32 v77, v69
	v_permlane32_swap_b32_e32 v73, v65
	v_permlane16_swap_b32_e32 v76, v72
	v_permlane16_swap_b32_e32 v68, v64
	v_permlane16_swap_b32_e32 v77, v73
	v_permlane16_swap_b32_e32 v69, v65
	global_store_dwordx2 v[176:177], v[76:77], off offset:256
	global_store_dwordx2 v[178:179], v[72:73], off offset:256
	global_store_dwordx2 v[184:185], v[68:69], off offset:256
	global_store_dwordx2 v[186:187], v[64:65], off offset:256
	v_mov_b32_e32 v180, 0x110000
	v_lshl_add_u64 v[176:177], v[174:175], 0, v[180:181]
	v_mov_b32_e32 v180, 0x121000
	v_lshl_add_u64 v[178:179], v[174:175], 0, v[180:181]
	v_mov_b32_e32 v180, 0x132000
	v_lshl_add_u64 v[184:185], v[174:175], 0, v[180:181]
	v_mov_b32_e32 v180, 0x143000
	v_lshl_add_u64 v[186:187], v[174:175], 0, v[180:181]
	v_cvt_pk_bf16_f32 v60, v60, v61
	v_cvt_pk_bf16_f32 v62, v62, v63
	v_cvt_pk_bf16_f32 v56, v56, v57
	v_cvt_pk_bf16_f32 v58, v58, v59
	v_mov_b32_dpp v61, v60 quad_perm:[1,0,3,2] row_mask:0xf bank_mask:0xf
	v_mov_b32_dpp v63, v62 quad_perm:[1,0,3,2] row_mask:0xf bank_mask:0xf
	v_mov_b32_dpp v57, v56 quad_perm:[1,0,3,2] row_mask:0xf bank_mask:0xf
	v_mov_b32_dpp v59, v58 quad_perm:[1,0,3,2] row_mask:0xf bank_mask:0xf
	v_perm_b32 v60, v61, v60, v182
	v_perm_b32 v62, v63, v62, v182
	v_perm_b32 v56, v57, v56, v182
	v_perm_b32 v58, v59, v58, v182
	v_cndmask_b32_e32 v61, v62, v60, vcc
	v_cndmask_b32_e32 v57, v58, v56, vcc
	s_nop 1
	v_mov_b32_dpp v63, v61 quad_perm:[2,3,0,1] row_mask:0xf bank_mask:0xf
	v_mov_b32_dpp v59, v57 quad_perm:[2,3,0,1] row_mask:0xf bank_mask:0xf
	v_cndmask_b32_e32 v60, v60, v63, vcc
	v_cndmask_b32_e32 v61, v63, v62, vcc
	v_cndmask_b32_e32 v56, v56, v59, vcc
	v_cndmask_b32_e32 v57, v59, v58, vcc
	v_cvt_pk_bf16_f32 v52, v52, v53
	v_cvt_pk_bf16_f32 v54, v54, v55
	v_cvt_pk_bf16_f32 v48, v48, v49
	v_cvt_pk_bf16_f32 v50, v50, v51
	v_mov_b32_dpp v53, v52 quad_perm:[1,0,3,2] row_mask:0xf bank_mask:0xf
	v_mov_b32_dpp v55, v54 quad_perm:[1,0,3,2] row_mask:0xf bank_mask:0xf
	v_mov_b32_dpp v49, v48 quad_perm:[1,0,3,2] row_mask:0xf bank_mask:0xf
	v_mov_b32_dpp v51, v50 quad_perm:[1,0,3,2] row_mask:0xf bank_mask:0xf
	v_perm_b32 v52, v53, v52, v182
	v_perm_b32 v54, v55, v54, v182
	v_perm_b32 v48, v49, v48, v182
	v_perm_b32 v50, v51, v50, v182
	v_cndmask_b32_e32 v53, v54, v52, vcc
	v_cndmask_b32_e32 v49, v50, v48, vcc
	s_nop 1
	v_mov_b32_dpp v55, v53 quad_perm:[2,3,0,1] row_mask:0xf bank_mask:0xf
	v_mov_b32_dpp v51, v49 quad_perm:[2,3,0,1] row_mask:0xf bank_mask:0xf
	v_cndmask_b32_e32 v52, v52, v55, vcc
	v_cndmask_b32_e32 v53, v55, v54, vcc
	v_cndmask_b32_e32 v48, v48, v51, vcc
	v_cndmask_b32_e32 v49, v51, v50, vcc
	s_nop 1
	v_permlane32_swap_b32_e32 v60, v52
	v_permlane32_swap_b32_e32 v56, v48
	v_permlane32_swap_b32_e32 v61, v53
	v_permlane32_swap_b32_e32 v57, v49
	v_permlane16_swap_b32_e32 v60, v56
	v_permlane16_swap_b32_e32 v52, v48
	v_permlane16_swap_b32_e32 v61, v57
	v_permlane16_swap_b32_e32 v53, v49
	global_store_dwordx2 v[176:177], v[60:61], off
	global_store_dwordx2 v[178:179], v[56:57], off
	global_store_dwordx2 v[184:185], v[52:53], off
	global_store_dwordx2 v[186:187], v[48:49], off
	v_cvt_pk_bf16_f32 v44, v44, v45
	v_cvt_pk_bf16_f32 v46, v46, v47
	v_cvt_pk_bf16_f32 v40, v40, v41
	v_cvt_pk_bf16_f32 v42, v42, v43
	v_mov_b32_dpp v45, v44 quad_perm:[1,0,3,2] row_mask:0xf bank_mask:0xf
	v_mov_b32_dpp v47, v46 quad_perm:[1,0,3,2] row_mask:0xf bank_mask:0xf
	v_mov_b32_dpp v41, v40 quad_perm:[1,0,3,2] row_mask:0xf bank_mask:0xf
	v_mov_b32_dpp v43, v42 quad_perm:[1,0,3,2] row_mask:0xf bank_mask:0xf
	v_perm_b32 v44, v45, v44, v182
	v_perm_b32 v46, v47, v46, v182
	v_perm_b32 v40, v41, v40, v182
	v_perm_b32 v42, v43, v42, v182
	v_cndmask_b32_e32 v45, v46, v44, vcc
	v_cndmask_b32_e32 v41, v42, v40, vcc
	s_nop 1
	v_mov_b32_dpp v47, v45 quad_perm:[2,3,0,1] row_mask:0xf bank_mask:0xf
	v_mov_b32_dpp v43, v41 quad_perm:[2,3,0,1] row_mask:0xf bank_mask:0xf
	v_cndmask_b32_e32 v44, v44, v47, vcc
	v_cndmask_b32_e32 v45, v47, v46, vcc
	v_cndmask_b32_e32 v40, v40, v43, vcc
	v_cndmask_b32_e32 v41, v43, v42, vcc
	v_cvt_pk_bf16_f32 v36, v36, v37
	v_cvt_pk_bf16_f32 v38, v38, v39
	v_cvt_pk_bf16_f32 v32, v32, v33
	v_cvt_pk_bf16_f32 v34, v34, v35
	v_mov_b32_dpp v37, v36 quad_perm:[1,0,3,2] row_mask:0xf bank_mask:0xf
	v_mov_b32_dpp v39, v38 quad_perm:[1,0,3,2] row_mask:0xf bank_mask:0xf
	v_mov_b32_dpp v33, v32 quad_perm:[1,0,3,2] row_mask:0xf bank_mask:0xf
	v_mov_b32_dpp v35, v34 quad_perm:[1,0,3,2] row_mask:0xf bank_mask:0xf
	v_perm_b32 v36, v37, v36, v182
	v_perm_b32 v38, v39, v38, v182
	v_perm_b32 v32, v33, v32, v182
	v_perm_b32 v34, v35, v34, v182
	v_cndmask_b32_e32 v37, v38, v36, vcc
	v_cndmask_b32_e32 v33, v34, v32, vcc
	s_nop 1
	v_mov_b32_dpp v39, v37 quad_perm:[2,3,0,1] row_mask:0xf bank_mask:0xf
	v_mov_b32_dpp v35, v33 quad_perm:[2,3,0,1] row_mask:0xf bank_mask:0xf
	v_cndmask_b32_e32 v36, v36, v39, vcc
	v_cndmask_b32_e32 v37, v39, v38, vcc
	v_cndmask_b32_e32 v32, v32, v35, vcc
	v_cndmask_b32_e32 v33, v35, v34, vcc
	s_nop 1
	v_permlane32_swap_b32_e32 v44, v36
	v_permlane32_swap_b32_e32 v40, v32
	v_permlane32_swap_b32_e32 v45, v37
	v_permlane32_swap_b32_e32 v41, v33
	v_permlane16_swap_b32_e32 v44, v40
	v_permlane16_swap_b32_e32 v36, v32
	v_permlane16_swap_b32_e32 v45, v41
	v_permlane16_swap_b32_e32 v37, v33
	global_store_dwordx2 v[176:177], v[44:45], off offset:256
	global_store_dwordx2 v[178:179], v[40:41], off offset:256
	global_store_dwordx2 v[184:185], v[36:37], off offset:256
	global_store_dwordx2 v[186:187], v[32:33], off offset:256
	v_mov_b32_e32 v180, 0x118800
	v_lshl_add_u64 v[176:177], v[174:175], 0, v[180:181]
	v_mov_b32_e32 v180, 0x129800
	v_lshl_add_u64 v[178:179], v[174:175], 0, v[180:181]
	v_mov_b32_e32 v180, 0x13a800
	v_lshl_add_u64 v[184:185], v[174:175], 0, v[180:181]
	v_mov_b32_e32 v180, 0x14b800
	v_lshl_add_u64 v[186:187], v[174:175], 0, v[180:181]
	v_cvt_pk_bf16_f32 v28, v28, v29
	v_cvt_pk_bf16_f32 v30, v30, v31
	v_cvt_pk_bf16_f32 v24, v24, v25
	v_cvt_pk_bf16_f32 v26, v26, v27
	v_mov_b32_dpp v29, v28 quad_perm:[1,0,3,2] row_mask:0xf bank_mask:0xf
	v_mov_b32_dpp v31, v30 quad_perm:[1,0,3,2] row_mask:0xf bank_mask:0xf
	v_mov_b32_dpp v25, v24 quad_perm:[1,0,3,2] row_mask:0xf bank_mask:0xf
	v_mov_b32_dpp v27, v26 quad_perm:[1,0,3,2] row_mask:0xf bank_mask:0xf
	v_perm_b32 v28, v29, v28, v182
	v_perm_b32 v30, v31, v30, v182
	v_perm_b32 v24, v25, v24, v182
	v_perm_b32 v26, v27, v26, v182
	v_cndmask_b32_e32 v29, v30, v28, vcc
	v_cndmask_b32_e32 v25, v26, v24, vcc
	s_nop 1
	v_mov_b32_dpp v31, v29 quad_perm:[2,3,0,1] row_mask:0xf bank_mask:0xf
	v_mov_b32_dpp v27, v25 quad_perm:[2,3,0,1] row_mask:0xf bank_mask:0xf
	v_cndmask_b32_e32 v28, v28, v31, vcc
	v_cndmask_b32_e32 v29, v31, v30, vcc
	v_cndmask_b32_e32 v24, v24, v27, vcc
	v_cndmask_b32_e32 v25, v27, v26, vcc
	v_cvt_pk_bf16_f32 v20, v20, v21
	v_cvt_pk_bf16_f32 v22, v22, v23
	v_cvt_pk_bf16_f32 v16, v16, v17
	v_cvt_pk_bf16_f32 v18, v18, v19
	v_mov_b32_dpp v21, v20 quad_perm:[1,0,3,2] row_mask:0xf bank_mask:0xf
	v_mov_b32_dpp v23, v22 quad_perm:[1,0,3,2] row_mask:0xf bank_mask:0xf
	v_mov_b32_dpp v17, v16 quad_perm:[1,0,3,2] row_mask:0xf bank_mask:0xf
	v_mov_b32_dpp v19, v18 quad_perm:[1,0,3,2] row_mask:0xf bank_mask:0xf
	v_perm_b32 v20, v21, v20, v182
	v_perm_b32 v22, v23, v22, v182
	v_perm_b32 v16, v17, v16, v182
	v_perm_b32 v18, v19, v18, v182
	v_cndmask_b32_e32 v21, v22, v20, vcc
	v_cndmask_b32_e32 v17, v18, v16, vcc
	s_nop 1
	v_mov_b32_dpp v23, v21 quad_perm:[2,3,0,1] row_mask:0xf bank_mask:0xf
	v_mov_b32_dpp v19, v17 quad_perm:[2,3,0,1] row_mask:0xf bank_mask:0xf
	v_cndmask_b32_e32 v20, v20, v23, vcc
	v_cndmask_b32_e32 v21, v23, v22, vcc
	v_cndmask_b32_e32 v16, v16, v19, vcc
	v_cndmask_b32_e32 v17, v19, v18, vcc
	s_nop 1
	v_permlane32_swap_b32_e32 v28, v20
	v_permlane32_swap_b32_e32 v24, v16
	v_permlane32_swap_b32_e32 v29, v21
	v_permlane32_swap_b32_e32 v25, v17
	v_permlane16_swap_b32_e32 v28, v24
	v_permlane16_swap_b32_e32 v20, v16
	v_permlane16_swap_b32_e32 v29, v25
	v_permlane16_swap_b32_e32 v21, v17
	global_store_dwordx2 v[176:177], v[28:29], off
	global_store_dwordx2 v[178:179], v[24:25], off
	global_store_dwordx2 v[184:185], v[20:21], off
	global_store_dwordx2 v[186:187], v[16:17], off
	v_cvt_pk_bf16_f32 v12, v12, v13
	v_cvt_pk_bf16_f32 v14, v14, v15
	v_cvt_pk_bf16_f32 v8, v8, v9
	v_cvt_pk_bf16_f32 v10, v10, v11
	v_mov_b32_dpp v13, v12 quad_perm:[1,0,3,2] row_mask:0xf bank_mask:0xf
	v_mov_b32_dpp v15, v14 quad_perm:[1,0,3,2] row_mask:0xf bank_mask:0xf
	v_mov_b32_dpp v9, v8 quad_perm:[1,0,3,2] row_mask:0xf bank_mask:0xf
	v_mov_b32_dpp v11, v10 quad_perm:[1,0,3,2] row_mask:0xf bank_mask:0xf
	v_perm_b32 v12, v13, v12, v182
	v_perm_b32 v14, v15, v14, v182
	v_perm_b32 v8, v9, v8, v182
	v_perm_b32 v10, v11, v10, v182
	v_cndmask_b32_e32 v13, v14, v12, vcc
	v_cndmask_b32_e32 v9, v10, v8, vcc
	s_nop 1
	v_mov_b32_dpp v15, v13 quad_perm:[2,3,0,1] row_mask:0xf bank_mask:0xf
	v_mov_b32_dpp v11, v9 quad_perm:[2,3,0,1] row_mask:0xf bank_mask:0xf
	v_cndmask_b32_e32 v12, v12, v15, vcc
	v_cndmask_b32_e32 v13, v15, v14, vcc
	v_cndmask_b32_e32 v8, v8, v11, vcc
	v_cndmask_b32_e32 v9, v11, v10, vcc
	v_cvt_pk_bf16_f32 v4, v4, v5
	v_cvt_pk_bf16_f32 v6, v6, v7
	v_cvt_pk_bf16_f32 v0, v0, v1
	v_cvt_pk_bf16_f32 v2, v2, v3
	v_mov_b32_dpp v5, v4 quad_perm:[1,0,3,2] row_mask:0xf bank_mask:0xf
	v_mov_b32_dpp v7, v6 quad_perm:[1,0,3,2] row_mask:0xf bank_mask:0xf
	v_mov_b32_dpp v1, v0 quad_perm:[1,0,3,2] row_mask:0xf bank_mask:0xf
	v_mov_b32_dpp v3, v2 quad_perm:[1,0,3,2] row_mask:0xf bank_mask:0xf
	v_perm_b32 v4, v5, v4, v182
	v_perm_b32 v6, v7, v6, v182
	v_perm_b32 v0, v1, v0, v182
	v_perm_b32 v2, v3, v2, v182
	v_cndmask_b32_e32 v5, v6, v4, vcc
	v_cndmask_b32_e32 v1, v2, v0, vcc
	s_nop 1
	v_mov_b32_dpp v7, v5 quad_perm:[2,3,0,1] row_mask:0xf bank_mask:0xf
	v_mov_b32_dpp v3, v1 quad_perm:[2,3,0,1] row_mask:0xf bank_mask:0xf
	v_cndmask_b32_e32 v4, v4, v7, vcc
	v_cndmask_b32_e32 v5, v7, v6, vcc
	v_cndmask_b32_e32 v0, v0, v3, vcc
	v_cndmask_b32_e32 v1, v3, v2, vcc
	s_nop 1
	v_permlane32_swap_b32_e32 v12, v4
	v_permlane32_swap_b32_e32 v8, v0
	v_permlane32_swap_b32_e32 v13, v5
	v_permlane32_swap_b32_e32 v9, v1
	v_permlane16_swap_b32_e32 v12, v8
	v_permlane16_swap_b32_e32 v4, v0
	v_permlane16_swap_b32_e32 v13, v9
	v_permlane16_swap_b32_e32 v5, v1
	global_store_dwordx2 v[176:177], v[12:13], off offset:256
	global_store_dwordx2 v[178:179], v[8:9], off offset:256
	global_store_dwordx2 v[184:185], v[4:5], off offset:256
	global_store_dwordx2 v[186:187], v[0:1], off offset:256
	s_branch .LBB0_278
